# d4 with the attention mid-step barrier moved after the last PV MFMA (+vmcnt(2) before it): PV-heavy half beside QK/LDS-latency half
# speedup vs baseline: 1.0092x; 1.0092x over previous
; __device__ __forceinline__ unsigned cvtpk(float lo, float hi) { f32x2 v = {lo, hi}; bf16x2_t b = __builtin_convertvector(v, bf16x2_t); return __builtin_bit_cast(unsigned, b); }
; __device__ __forceinline__ float fast_exp2(float x) { return __builtin_amdgcn_exp2f(x); }
; template <bool QK, bool PV> ...
;     ...
;     if constexpr (PV) { AT_TR4(0, 0); AT_TR4(1, 1);
;         const bf16x8 ones = (bf16x8){0x3f80, 0x3f80, 0x3f80, 0x3f80, 0x3f80, 0x3f80, 0x3f80, 0x3f80};
; #pragma unroll
;         for (int c = 0; c < 2; ++c)
; #pragma unroll
;             for (int si = 0; si < 2; ++si) ol[c] = __builtin_amdgcn_mfma_f32_16x16x32_bf16(ones, pf[c][si], ol[c], 0, 0, 0); }
; #pragma unroll
;     for (int dt = 0; dt < 8; ++dt) {
;         if constexpr (PV) {
;             const int cb = dt % 3;
;             if (dt < 6) { AT_TR4((dt + 2) % 3, dt + 2); asm volatile("s_waitcnt lgkmcnt(8)" : "+v"(r[cb][0]), "+v"(r[cb][1]), "+v"(r[cb][2]), "+v"(r[cb][3])); }
;             else if (dt == 6) asm volatile("s_waitcnt lgkmcnt(4)" : "+v"(r[cb][0]), "+v"(r[cb][1]), "+v"(r[cb][2]), "+v"(r[cb][3]));
;             else asm volatile("s_waitcnt lgkmcnt(0)" : "+v"(r[cb][0]), "+v"(r[cb][1]), "+v"(r[cb][2]), "+v"(r[cb][3]));
; #pragma unroll
;             for (int si = 0; si < 2; ++si) {
;                 const s16x4 lo = r[cb][2 * si], hi = r[cb][2 * si + 1];
;                 const bf16x8 vf = (bf16x8){lo[0], lo[1], lo[2], lo[3], hi[0], hi[1], hi[2], hi[3]};
;                 o[0][dt] = __builtin_amdgcn_mfma_f32_16x16x32_bf16(vf, pf[0][si], o[0][dt], 0, 0, 0);
;                 o[1][dt] = __builtin_amdgcn_mfma_f32_16x16x32_bf16(vf, pf[1][si], o[1][dt], 0, 0, 0);
;             }
;         }
;         {
;             const int c = dt >> 2, kt = dt & 3;
; #pragma unroll
;             for (int j = 0; j < 4; ++j) s[c][kt][j] = fast_exp2(s[c][kt][j]);
;             if (kt & 1) { const int si = kt >> 1;
;                 u32x4 wv; wv.x = cvtpk(s[c][2 * si][0], s[c][2 * si][1]); wv.y = cvtpk(s[c][2 * si][2], s[c][2 * si][3]);
;                 wv.z = cvtpk(s[c][2 * si + 1][0], s[c][2 * si + 1][1]); wv.w = cvtpk(s[c][2 * si + 1][2], s[c][2 * si + 1][3]);
;                 pn[c][si] = __builtin_bit_cast(bf16x8, wv); }
.LBB0_518:
	v_mov_b64_e32 v[218:219], s[6:7]
	v_mov_b64_e32 v[216:217], s[4:5]
	s_and_b32 s2, s55, 0xc000
	s_add_i32 s2, s2, 0
	s_add_i32 s2, s2, 0xc000
	v_add_u32_e32 v228, s2, v186
	v_mfma_f32_16x16x32_bf16 v[134:137], v[216:219], v[58:61], v[134:137]
	ds_read_b64_tr_b16 v[220:221], v228 offset:0
	ds_read_b64_tr_b16 v[222:223], v228 offset:0x1000
	ds_read_b64_tr_b16 v[224:225], v228 offset:0x2000
	v_mfma_f32_16x16x32_bf16 v[130:133], v[216:219], v[42:45], v[130:133]
	ds_read_b64_tr_b16 v[226:227], v228 offset:0x3000
	v_add_u32_e32 v236, s2, v187
	ds_read_b64_tr_b16 v[228:229], v236 offset:0
	v_mfma_f32_16x16x32_bf16 v[134:137], v[216:219], v[34:37], v[134:137]
	ds_read_b64_tr_b16 v[230:231], v236 offset:0x1000
	ds_read_b64_tr_b16 v[232:233], v236 offset:0x2000
	ds_read_b64_tr_b16 v[234:235], v236 offset:0x3000
	v_mfma_f32_16x16x32_bf16 v[130:133], v[216:219], v[18:21], v[130:133]
	v_add_u32_e32 v240, s2, v188
	ds_read_b64_tr_b16 v[216:217], v240 offset:0
	ds_read_b64_tr_b16 v[218:219], v240 offset:0x1000
	ds_read_b64_tr_b16 v[236:237], v240 offset:0x2000
	ds_read_b64_tr_b16 v[238:239], v240 offset:0x3000
	s_waitcnt lgkmcnt(8)
	v_add_u32_e32 v240, s2, v189
	v_mfma_f32_16x16x32_bf16 v[126:129], v[220:223], v[58:61], v[126:129]
	v_exp_f32_e32 v241, v28
	v_exp_f32_e32 v242, v29
	s_addk_i32 s55, 0x4000
	v_mfma_f32_16x16x32_bf16 v[122:125], v[220:223], v[42:45], v[122:125]
	ds_read_b64_tr_b16 v[220:221], v240 offset:0
	ds_read_b64_tr_b16 v[222:223], v240 offset:0x1000
	s_add_i32 s60, s60, 1
	v_mfma_f32_16x16x32_bf16 v[126:129], v[224:227], v[34:37], v[126:129]
	v_mfma_f32_16x16x32_bf16 v[122:125], v[224:227], v[18:21], v[122:125]
	ds_read_b64_tr_b16 v[224:225], v240 offset:0x2000
	ds_read_b64_tr_b16 v[226:227], v240 offset:0x3000
	s_waitcnt lgkmcnt(8)
	v_add_u32_e32 v240, s2, v190
	v_mfma_f32_16x16x32_bf16 v[114:117], v[228:231], v[58:61], v[114:117]
	v_mfma_f32_16x16x32_bf16 v[118:121], v[228:231], v[42:45], v[118:121]
	ds_read_b64_tr_b16 v[228:229], v240 offset:0
	ds_read_b64_tr_b16 v[230:231], v240 offset:0x1000
	v_mfma_f32_16x16x32_bf16 v[114:117], v[232:235], v[34:37], v[114:117]
	v_mfma_f32_16x16x32_bf16 v[118:121], v[232:235], v[18:21], v[118:121]
	ds_read_b64_tr_b16 v[232:233], v240 offset:0x2000
	ds_read_b64_tr_b16 v[234:235], v240 offset:0x3000
	s_waitcnt lgkmcnt(8)
	v_add_u32_e32 v240, s2, v191
	v_mfma_f32_16x16x32_bf16 v[106:109], v[216:219], v[58:61], v[106:109]
	v_mfma_f32_16x16x32_bf16 v[110:113], v[216:219], v[42:45], v[110:113]
	ds_read_b64_tr_b16 v[216:217], v240 offset:0
	ds_read_b64_tr_b16 v[218:219], v240 offset:0x1000
	v_mfma_f32_16x16x32_bf16 v[106:109], v[236:239], v[34:37], v[106:109]
	v_mfma_f32_16x16x32_bf16 v[110:113], v[236:239], v[18:21], v[110:113]
	ds_read_b64_tr_b16 v[236:237], v240 offset:0x2000
	ds_read_b64_tr_b16 v[238:239], v240 offset:0x3000
	s_waitcnt lgkmcnt(8)
	v_add_u32_e32 v240, s2, v192
	v_mfma_f32_16x16x32_bf16 v[98:101], v[220:223], v[58:61], v[98:101]
	v_mfma_f32_16x16x32_bf16 v[102:105], v[220:223], v[42:45], v[102:105]
	ds_read_b64_tr_b16 v[220:221], v240 offset:0
	ds_read_b64_tr_b16 v[222:223], v240 offset:0x1000
	v_mfma_f32_16x16x32_bf16 v[98:101], v[224:227], v[34:37], v[98:101]
	v_mfma_f32_16x16x32_bf16 v[102:105], v[224:227], v[18:21], v[102:105]
	ds_read_b64_tr_b16 v[224:225], v240 offset:0x2000
	ds_read_b64_tr_b16 v[226:227], v240 offset:0x3000
	s_waitcnt lgkmcnt(8)
	v_add_u32_e32 v240, s2, v193
	v_mfma_f32_16x16x32_bf16 v[78:81], v[228:231], v[58:61], v[78:81]
	s_add_i32 s2, s61, 0
	s_cmp_lg_u32 s54, s60
	v_mfma_f32_16x16x32_bf16 v[82:85], v[228:231], v[42:45], v[82:85]
	ds_read_b64_tr_b16 v[228:229], v240 offset:0
	ds_read_b64_tr_b16 v[230:231], v240 offset:0x1000
	v_mfma_f32_16x16x32_bf16 v[78:81], v[232:235], v[34:37], v[78:81]
	v_mfma_f32_16x16x32_bf16 v[82:85], v[232:235], v[18:21], v[82:85]
	ds_read_b64_tr_b16 v[232:233], v240 offset:0x2000
	ds_read_b64_tr_b16 v[234:235], v240 offset:0x3000
	s_waitcnt lgkmcnt(8)
	s_waitcnt lgkmcnt(4)
	v_exp_f32_e32 v240, v22
	v_mfma_f32_16x16x32_bf16 v[54:57], v[220:223], v[58:61], v[54:57]
	s_waitcnt lgkmcnt(0)
	v_mfma_f32_16x16x32_bf16 v[50:53], v[220:223], v[42:45], v[50:53]
	v_exp_f32_e32 v220, v88
	v_exp_f32_e32 v221, v89
	v_exp_f32_e32 v222, v90
	v_mfma_f32_16x16x32_bf16 v[54:57], v[224:227], v[34:37], v[54:57]
	v_exp_f32_e32 v223, v91
	v_mfma_f32_16x16x32_bf16 v[50:53], v[224:227], v[18:21], v[50:53]
	v_exp_f32_e32 v224, v94
	v_add_u32_e32 v94, s2, v182
	v_exp_f32_e32 v225, v95
	v_mfma_f32_16x16x32_bf16 v[66:69], v[216:219], v[58:61], v[66:69]
	v_exp_f32_e32 v226, v96
	v_exp_f32_e32 v95, v38
	v_exp_f32_e32 v96, v39
	v_mfma_f32_16x16x32_bf16 v[30:33], v[228:231], v[58:61], v[30:33]
	ds_read_b128 v[58:61], v94
	v_exp_f32_e32 v227, v97
	v_mfma_f32_16x16x32_bf16 v[70:73], v[216:219], v[42:45], v[70:73]
	v_exp_f32_e32 v216, v74
	v_exp_f32_e32 v217, v75
	v_exp_f32_e32 v218, v76
	v_mfma_f32_16x16x32_bf16 v[42:45], v[228:231], v[42:45], v[46:49]
	v_add_u32_e32 v230, s2, v183
	v_add_u32_e32 v231, s2, v184
	v_exp_f32_e32 v219, v77
	v_mfma_f32_16x16x32_bf16 v[66:69], v[236:239], v[34:37], v[66:69]
	v_exp_f32_e32 v228, v23
	v_exp_f32_e32 v229, v24
	v_mfma_f32_16x16x32_bf16 v[30:33], v[232:235], v[34:37], v[30:33]
	ds_read_b128 v[34:37], v230
	s_waitcnt lgkmcnt(0)
	v_mfma_f32_16x16x32_bf16 v[58:61], v[58:61], v[2:5], v[146:149]
	v_mfma_f32_16x16x32_bf16 v[70:73], v[236:239], v[18:21], v[70:73]
	v_exp_f32_e32 v236, v86
	v_exp_f32_e32 v237, v87
	v_exp_f32_e32 v238, v92
	v_mfma_f32_16x16x32_bf16 v[46:49], v[232:235], v[18:21], v[42:45]
	s_waitcnt vmcnt(2)
	s_barrier
; #define LAS __attribute__((address_space(3)))
; #define AT_STAGE(gbase, so, i, ldsoff) do { const int _ii = (i) < NT ? (i) : NT - 1; const size_t _go = (size_t)((tstart + _ii) & tmask) * (64 * 1024); _Pragma("unroll") for (int _i = 0; _i < 2; ++_i) \
;         __builtin_amdgcn_global_load_lds((const unsigned*)((gbase) + _go + (so)[_i]), (LAS unsigned*)(lds + (ldsoff) + (2 * w + _i) * 1024), 16, 0, 0); } while (0)
; #define AT_BAR(N) asm volatile("s_waitcnt vmcnt(" #N ") lgkmcnt(0)\n\ts_barrier" ::: "memory")
; template <bool QK, bool PV> ...
;     ...
;     for (int c = 0; c < 2; ++c)
; #pragma unroll
;         for (int si = 0; si < 2; ++si) pf[c][si] = pn[c][si];
;     if constexpr (QK) {
; #pragma unroll
;         for (int kt = 0; kt < 4; ++kt)
; #pragma unroll
;             for (int c = 0; c < 2; ++c) {
;                 f32x4 a = tbv[kt];
; #pragma unroll
;                 for (int kk = 0; kk < 2; ++kk) { const bf16x8 kf = *(const LAS bf16x8*)(kbuf + kfo[c][kk] + kt * 4096); a = __builtin_amdgcn_mfma_f32_16x16x32_bf16(kf, qf[c][kk], a, 0, 0, 0); }
;                 s[c][kt] = a;
;             }
;     }
; __device__ __forceinline__ void attn_unit(LAS unsigned char* lds, int seq, int h, int qb, bf16_t* UQ, const bf16_t* KB, const bf16_t* VB, const float* rel_bias, const float* subln, float lam, float bmax) {
;     ...
;     for (int i = 1; i < NT - 1; ++i) {
;         AT_STAGE(kg, kso, i + 3, k_i); AT_STAGE(vg, vso, i + 2, AT_V0 + ((i + 2) & 3) * AT_TILE);
;         AT_TB((tstart + i + 1) & tmask);
;         attn_step<true, true>(lds + k_n, lds0 + AT_V0 + ((i - 1) & 3) * AT_TILE, kfo, vo, qf, s, pf, o, ol, tbv);
;         AT_BAR(4);
;         { const int tmp = k_i; k_i = k_n; k_n = k_p; k_p = tmp; }
	s_add_i32 s99, s60, 3
	s_min_u32 s99, s99, s45
	s_add_i32 s99, s99, s46
	s_and_b32 s99, s99, s45
	s_lshl_b32 s99, s99, 16
	s_add_u32 s100, s47, s99
	s_addc_u32 s101, s48, 0
	s_add_i32 s99, s49, s59
	s_mov_b32 m0, s99
	s_nop 0
	global_load_lds_dwordx4 v154, s[100:101]
	s_add_i32 m0, s99, 0x400
	s_nop 0
	global_load_lds_dwordx4 v166, s[100:101]
	s_cmp_lg_u32 s54, s60
	ds_read_b128 v[18:21], v231
	s_nop 1
	ds_read_b128 v[42:45], v94 offset:4096
	v_add_u32_e32 v232, s2, v185
	v_exp_f32_e32 v239, v93
	ds_read_b128 v[86:89], v232
	ds_read_b128 v[90:93], v230 offset:4096
	v_mfma_f32_16x16x32_bf16 v[74:77], v[34:37], v[6:9], v[58:61]
	ds_read_b128 v[34:37], v231 offset:4096
	v_exp_f32_e32 v233, v25
	v_exp_f32_e32 v234, v26
	s_waitcnt lgkmcnt(0)
	v_mfma_f32_16x16x32_bf16 v[18:21], v[18:21], v[10:13], v[146:149]
	ds_read_b128 v[58:61], v232 offset:4096
	v_exp_f32_e32 v235, v27
	v_mfma_f32_16x16x32_bf16 v[22:25], v[86:89], v[14:17], v[18:21]
	v_mfma_f32_16x16x32_bf16 v[18:21], v[42:45], v[2:5], v[138:141]
	v_exp_f32_e32 v42, v40
	v_exp_f32_e32 v43, v41
	ds_read_b128 v[38:41], v94 offset:8192
	v_mfma_f32_16x16x32_bf16 v[26:29], v[34:37], v[10:13], v[138:141]
	ds_read_b128 v[34:37], v230 offset:8192
	v_exp_f32_e32 v44, v62
	v_exp_f32_e32 v45, v65
	v_mfma_f32_16x16x32_bf16 v[86:89], v[90:93], v[6:9], v[18:21]
	s_nop 2
	v_exp_f32_e32 v20, v63
	v_exp_f32_e32 v21, v64
	v_cvt_pk_bf16_f32 v18, v95, v96
	s_waitcnt lgkmcnt(0)
	v_mfma_f32_16x16x32_bf16 v[26:29], v[58:61], v[14:17], v[26:29]
	ds_read_b128 v[58:61], v231 offset:8192
	ds_read_b128 v[62:65], v94 offset:12288
	ds_read_b128 v[94:97], v232 offset:8192
	ds_read_b128 v[138:141], v230 offset:12288
	ds_read_b128 v[146:149], v231 offset:12288
	v_mfma_f32_16x16x32_bf16 v[38:41], v[38:41], v[2:5], v[150:153]
	v_cvt_pk_bf16_f32 v19, v42, v43
	v_cvt_pk_bf16_f32 v20, v44, v20
	v_cvt_pk_bf16_f32 v21, v21, v45
	v_mfma_f32_16x16x32_bf16 v[90:93], v[34:37], v[6:9], v[38:41]
	v_cvt_pk_bf16_f32 v42, v240, v228
	v_cvt_pk_bf16_f32 v43, v229, v233
	v_cvt_pk_bf16_f32 v44, v234, v235
	s_waitcnt lgkmcnt(0)
	v_mfma_f32_16x16x32_bf16 v[34:37], v[58:61], v[10:13], v[150:153]
	v_cvt_pk_bf16_f32 v45, v241, v242
	v_cvt_pk_bf16_f32 v58, v216, v217
	v_cvt_pk_bf16_f32 v59, v218, v219
	ds_read_b128 v[150:153], v232 offset:12288
	v_mfma_f32_16x16x32_bf16 v[60:63], v[62:65], v[2:5], v[142:145]
	s_waitcnt vmcnt(4) lgkmcnt(0)
	s_barrier
	v_mfma_f32_16x16x32_bf16 v[38:41], v[94:97], v[14:17], v[34:37]
	v_mfma_f32_16x16x32_bf16 v[94:97], v[138:141], v[6:9], v[60:63]
	s_nop 1
	v_cvt_pk_bf16_f32 v34, v222, v223
	v_cvt_pk_bf16_f32 v35, v238, v239
	v_cvt_pk_bf16_f32 v36, v224, v225
	v_mfma_f32_16x16x32_bf16 v[62:65], v[146:149], v[10:13], v[142:145]
	v_cvt_pk_bf16_f32 v37, v226, v227
	v_cvt_pk_bf16_f32 v60, v236, v237
	v_cvt_pk_bf16_f32 v61, v220, v221
	s_waitcnt lgkmcnt(0)
	v_mfma_f32_16x16x32_bf16 v[62:65], v[150:153], v[14:17], v[62:65]
	s_cbranch_scc0 .LBB0_502
	s_mov_b32 s2, s59
	s_mov_b32 s59, s61
	s_branch .LBB0_514

; __device__ __forceinline__ unsigned cvtpk(float lo, float hi) { f32x2 v = {lo, hi}; bf16x2_t b = __builtin_convertvector(v, bf16x2_t); return __builtin_bit_cast(unsigned, b); }
; __device__ __forceinline__ float fast_exp2(float x) { return __builtin_amdgcn_exp2f(x); }
; template <bool QK, bool PV> ...
;     ...
;     if constexpr (PV) { AT_TR4(0, 0); AT_TR4(1, 1);
;         const bf16x8 ones = (bf16x8){0x3f80, 0x3f80, 0x3f80, 0x3f80, 0x3f80, 0x3f80, 0x3f80, 0x3f80};
; #pragma unroll
;         for (int c = 0; c < 2; ++c)
; #pragma unroll
;             for (int si = 0; si < 2; ++si) ol[c] = __builtin_amdgcn_mfma_f32_16x16x32_bf16(ones, pf[c][si], ol[c], 0, 0, 0); }
; #pragma unroll
;     for (int dt = 0; dt < 8; ++dt) {
;         if constexpr (PV) {
;             const int cb = dt % 3;
;             if (dt < 6) { AT_TR4((dt + 2) % 3, dt + 2); asm volatile("s_waitcnt lgkmcnt(8)" : "+v"(r[cb][0]), "+v"(r[cb][1]), "+v"(r[cb][2]), "+v"(r[cb][3])); }
;             else if (dt == 6) asm volatile("s_waitcnt lgkmcnt(4)" : "+v"(r[cb][0]), "+v"(r[cb][1]), "+v"(r[cb][2]), "+v"(r[cb][3]));
;             else asm volatile("s_waitcnt lgkmcnt(0)" : "+v"(r[cb][0]), "+v"(r[cb][1]), "+v"(r[cb][2]), "+v"(r[cb][3]));
; #pragma unroll
;             for (int si = 0; si < 2; ++si) {
;                 const s16x4 lo = r[cb][2 * si], hi = r[cb][2 * si + 1];
;                 const bf16x8 vf = (bf16x8){lo[0], lo[1], lo[2], lo[3], hi[0], hi[1], hi[2], hi[3]};
;                 o[0][dt] = __builtin_amdgcn_mfma_f32_16x16x32_bf16(vf, pf[0][si], o[0][dt], 0, 0, 0);
;                 o[1][dt] = __builtin_amdgcn_mfma_f32_16x16x32_bf16(vf, pf[1][si], o[1][dt], 0, 0, 0);
;             }
;         }
;         {
;             const int c = dt >> 2, kt = dt & 3;
; #pragma unroll
;             for (int j = 0; j < 4; ++j) s[c][kt][j] = fast_exp2(s[c][kt][j]);
;             if (kt & 1) { const int si = kt >> 1;
;                 u32x4 wv; wv.x = cvtpk(s[c][2 * si][0], s[c][2 * si][1]); wv.y = cvtpk(s[c][2 * si][2], s[c][2 * si][3]);
;                 wv.z = cvtpk(s[c][2 * si + 1][0], s[c][2 * si + 1][1]); wv.w = cvtpk(s[c][2 * si + 1][2], s[c][2 * si + 1][3]);
;                 pn[c][si] = __builtin_bit_cast(bf16x8, wv); }
.LBB0_538:
	v_mov_b64_e32 v[220:221], s[6:7]
	v_mov_b64_e32 v[218:219], s[4:5]
	s_and_b32 s2, s53, 0xc000
	s_add_i32 s2, s2, 0
	s_add_i32 s2, s2, 0xc000
	v_add_u32_e32 v217, s2, v175
	v_mfma_f32_16x16x32_bf16 v[134:137], v[218:221], v[58:61], v[134:137]
	ds_read_b64_tr_b16 v[222:223], v217 offset:0
	ds_read_b64_tr_b16 v[224:225], v217 offset:0x1000
	ds_read_b64_tr_b16 v[226:227], v217 offset:0x2000
	v_mfma_f32_16x16x32_bf16 v[130:133], v[218:221], v[42:45], v[130:133]
	ds_read_b64_tr_b16 v[228:229], v217 offset:0x3000
	v_add_u32_e32 v217, s2, v185
	ds_read_b64_tr_b16 v[230:231], v217 offset:0
	v_mfma_f32_16x16x32_bf16 v[134:137], v[218:221], v[34:37], v[134:137]
	ds_read_b64_tr_b16 v[232:233], v217 offset:0x1000
	ds_read_b64_tr_b16 v[234:235], v217 offset:0x2000
	ds_read_b64_tr_b16 v[236:237], v217 offset:0x3000
	v_mfma_f32_16x16x32_bf16 v[130:133], v[218:221], v[18:21], v[130:133]
	v_add_u32_e32 v217, s2, v186
	ds_read_b64_tr_b16 v[218:219], v217 offset:0
	ds_read_b64_tr_b16 v[220:221], v217 offset:0x1000
	ds_read_b64_tr_b16 v[238:239], v217 offset:0x2000
	ds_read_b64_tr_b16 v[240:241], v217 offset:0x3000
	s_waitcnt lgkmcnt(8)
	v_add_u32_e32 v217, s2, v187
	v_mfma_f32_16x16x32_bf16 v[126:129], v[222:225], v[58:61], v[126:129]
	v_exp_f32_e32 v242, v28
	v_exp_f32_e32 v243, v29
	s_addk_i32 s53, 0x4000
	v_mfma_f32_16x16x32_bf16 v[122:125], v[222:225], v[42:45], v[122:125]
	ds_read_b64_tr_b16 v[222:223], v217 offset:0
	ds_read_b64_tr_b16 v[224:225], v217 offset:0x1000
	v_mfma_f32_16x16x32_bf16 v[126:129], v[226:229], v[34:37], v[126:129]
	v_mfma_f32_16x16x32_bf16 v[122:125], v[226:229], v[18:21], v[122:125]
	ds_read_b64_tr_b16 v[226:227], v217 offset:0x2000
	ds_read_b64_tr_b16 v[228:229], v217 offset:0x3000
	s_waitcnt lgkmcnt(8)
	v_add_u32_e32 v217, s2, v188
	v_mfma_f32_16x16x32_bf16 v[114:117], v[230:233], v[58:61], v[114:117]
	v_mfma_f32_16x16x32_bf16 v[118:121], v[230:233], v[42:45], v[118:121]
	ds_read_b64_tr_b16 v[230:231], v217 offset:0
	ds_read_b64_tr_b16 v[232:233], v217 offset:0x1000
	v_mfma_f32_16x16x32_bf16 v[114:117], v[234:237], v[34:37], v[114:117]
	v_mfma_f32_16x16x32_bf16 v[118:121], v[234:237], v[18:21], v[118:121]
	ds_read_b64_tr_b16 v[234:235], v217 offset:0x2000
	ds_read_b64_tr_b16 v[236:237], v217 offset:0x3000
	s_waitcnt lgkmcnt(8)
	v_add_u32_e32 v217, s2, v189
	v_mfma_f32_16x16x32_bf16 v[106:109], v[218:221], v[58:61], v[106:109]
	v_mfma_f32_16x16x32_bf16 v[110:113], v[218:221], v[42:45], v[110:113]
	ds_read_b64_tr_b16 v[218:219], v217 offset:0
	ds_read_b64_tr_b16 v[220:221], v217 offset:0x1000
	v_mfma_f32_16x16x32_bf16 v[106:109], v[238:241], v[34:37], v[106:109]
	v_mfma_f32_16x16x32_bf16 v[110:113], v[238:241], v[18:21], v[110:113]
	ds_read_b64_tr_b16 v[238:239], v217 offset:0x2000
	ds_read_b64_tr_b16 v[240:241], v217 offset:0x3000
	s_waitcnt lgkmcnt(8)
	v_add_u32_e32 v217, s2, v190
	v_mfma_f32_16x16x32_bf16 v[98:101], v[222:225], v[58:61], v[98:101]
	v_mfma_f32_16x16x32_bf16 v[102:105], v[222:225], v[42:45], v[102:105]
	ds_read_b64_tr_b16 v[222:223], v217 offset:0
	ds_read_b64_tr_b16 v[224:225], v217 offset:0x1000
	v_mfma_f32_16x16x32_bf16 v[98:101], v[226:229], v[34:37], v[98:101]
	v_mfma_f32_16x16x32_bf16 v[102:105], v[226:229], v[18:21], v[102:105]
	ds_read_b64_tr_b16 v[226:227], v217 offset:0x2000
	ds_read_b64_tr_b16 v[228:229], v217 offset:0x3000
	s_waitcnt lgkmcnt(8)
	v_add_u32_e32 v217, s2, v191
	v_mfma_f32_16x16x32_bf16 v[78:81], v[230:233], v[58:61], v[78:81]
	s_add_i32 s2, s57, 0
	s_cmp_lg_u32 s56, 30
	v_mfma_f32_16x16x32_bf16 v[82:85], v[230:233], v[42:45], v[82:85]
	ds_read_b64_tr_b16 v[230:231], v217 offset:0
	ds_read_b64_tr_b16 v[232:233], v217 offset:0x1000
	v_mfma_f32_16x16x32_bf16 v[78:81], v[234:237], v[34:37], v[78:81]
	v_mfma_f32_16x16x32_bf16 v[82:85], v[234:237], v[18:21], v[82:85]
	ds_read_b64_tr_b16 v[234:235], v217 offset:0x2000
	ds_read_b64_tr_b16 v[236:237], v217 offset:0x3000
	s_waitcnt lgkmcnt(8)
	s_waitcnt lgkmcnt(4)
	v_exp_f32_e32 v217, v74
	v_mfma_f32_16x16x32_bf16 v[54:57], v[222:225], v[58:61], v[54:57]
	s_waitcnt lgkmcnt(0)
	v_mfma_f32_16x16x32_bf16 v[50:53], v[222:225], v[42:45], v[50:53]
	v_exp_f32_e32 v222, v88
	v_exp_f32_e32 v223, v89
	v_exp_f32_e32 v224, v90
	v_mfma_f32_16x16x32_bf16 v[54:57], v[226:229], v[34:37], v[54:57]
	v_exp_f32_e32 v225, v91
	v_mfma_f32_16x16x32_bf16 v[50:53], v[226:229], v[18:21], v[50:53]
	v_exp_f32_e32 v226, v94
	v_add_u32_e32 v94, s2, v176
	v_exp_f32_e32 v227, v95
	v_mfma_f32_16x16x32_bf16 v[66:69], v[218:221], v[58:61], v[66:69]
	v_exp_f32_e32 v228, v96
	v_exp_f32_e32 v95, v38
	v_exp_f32_e32 v96, v39
	v_mfma_f32_16x16x32_bf16 v[30:33], v[230:233], v[58:61], v[30:33]
	ds_read_b128 v[58:61], v94
	v_exp_f32_e32 v229, v97
	v_mfma_f32_16x16x32_bf16 v[70:73], v[218:221], v[42:45], v[70:73]
	v_exp_f32_e32 v218, v75
	v_exp_f32_e32 v219, v76
	v_exp_f32_e32 v220, v77
	v_mfma_f32_16x16x32_bf16 v[42:45], v[230:233], v[42:45], v[46:49]
	v_add_u32_e32 v232, s2, v182
	v_add_u32_e32 v233, s2, v183
	v_exp_f32_e32 v221, v86
	v_mfma_f32_16x16x32_bf16 v[66:69], v[238:241], v[34:37], v[66:69]
	v_exp_f32_e32 v230, v23
	v_exp_f32_e32 v231, v24
	v_mfma_f32_16x16x32_bf16 v[30:33], v[234:237], v[34:37], v[30:33]
	ds_read_b128 v[34:37], v232
	s_waitcnt lgkmcnt(0)
	v_mfma_f32_16x16x32_bf16 v[58:61], v[58:61], v[2:5], v[146:149]
	v_mfma_f32_16x16x32_bf16 v[70:73], v[238:241], v[18:21], v[70:73]
	v_exp_f32_e32 v238, v87
	v_exp_f32_e32 v239, v92
	v_exp_f32_e32 v240, v93
	v_mfma_f32_16x16x32_bf16 v[46:49], v[234:237], v[18:21], v[42:45]
	s_waitcnt vmcnt(2)
	s_barrier
; #define LAS __attribute__((address_space(3)))
; #define AT_STAGE(gbase, so, i, ldsoff) do { const int _ii = (i) < NT ? (i) : NT - 1; const size_t _go = (size_t)((tstart + _ii) & tmask) * (64 * 1024); _Pragma("unroll") for (int _i = 0; _i < 2; ++_i) \
;         __builtin_amdgcn_global_load_lds((const unsigned*)((gbase) + _go + (so)[_i]), (LAS unsigned*)(lds + (ldsoff) + (2 * w + _i) * 1024), 16, 0, 0); } while (0)
; #define AT_BAR(N) asm volatile("s_waitcnt vmcnt(" #N ") lgkmcnt(0)\n\ts_barrier" ::: "memory")
; template <bool QK, bool PV> ...
;     ...
;     for (int c = 0; c < 2; ++c)
; #pragma unroll
;         for (int si = 0; si < 2; ++si) pf[c][si] = pn[c][si];
;     if constexpr (QK) {
; #pragma unroll
;         for (int kt = 0; kt < 4; ++kt)
; #pragma unroll
;             for (int c = 0; c < 2; ++c) {
;                 f32x4 a = tbv[kt];
; #pragma unroll
;                 for (int kk = 0; kk < 2; ++kk) { const bf16x8 kf = *(const LAS bf16x8*)(kbuf + kfo[c][kk] + kt * 4096); a = __builtin_amdgcn_mfma_f32_16x16x32_bf16(kf, qf[c][kk], a, 0, 0, 0); }
;                 s[c][kt] = a;
;             }
;     }
; __device__ __forceinline__ void attn_unit(LAS unsigned char* lds, int seq, int h, int qb, bf16_t* UQ, const bf16_t* KB, const bf16_t* VB, const float* rel_bias, const float* subln, float lam, float bmax) {
;     ...
;     for (int i = 1; i < NT - 1; ++i) {
;         AT_STAGE(kg, kso, i + 3, k_i); AT_STAGE(vg, vso, i + 2, AT_V0 + ((i + 2) & 3) * AT_TILE);
;         AT_TB((tstart + i + 1) & tmask);
;         attn_step<true, true>(lds + k_n, lds0 + AT_V0 + ((i - 1) & 3) * AT_TILE, kfo, vo, qf, s, pf, o, ol, tbv);
;         AT_BAR(4);
;         { const int tmp = k_i; k_i = k_n; k_n = k_p; k_p = tmp; }
	s_min_u32 s99, s56, 28
	s_add_i32 s99, s52, s99
	s_lshl_b32 s99, s99, 16
	s_and_b32 s99, s99, 0x1f0000
	s_add_u32 s100, s45, s99
	s_addc_u32 s101, s46, 0
	s_add_i32 s99, s47, s55
	s_mov_b32 m0, s99
	s_nop 0
	global_load_lds_dwordx4 v154, s[100:101]
	s_add_i32 m0, s99, 0x400
	s_nop 0
	global_load_lds_dwordx4 v166, s[100:101]
	s_cmp_lg_u32 s56, 30
	ds_read_b128 v[18:21], v233
	s_nop 1
	ds_read_b128 v[42:45], v94 offset:4096
	v_add_u32_e32 v234, s2, v184
	ds_read_b128 v[86:89], v234
	ds_read_b128 v[90:93], v232 offset:4096
	v_mfma_f32_16x16x32_bf16 v[74:77], v[34:37], v[6:9], v[58:61]
	ds_read_b128 v[34:37], v233 offset:4096
	v_exp_f32_e32 v241, v22
	v_exp_f32_e32 v235, v25
	s_waitcnt lgkmcnt(0)
	v_mfma_f32_16x16x32_bf16 v[18:21], v[18:21], v[10:13], v[146:149]
	ds_read_b128 v[58:61], v234 offset:4096
	v_exp_f32_e32 v236, v26
	v_exp_f32_e32 v237, v27
	v_mfma_f32_16x16x32_bf16 v[22:25], v[86:89], v[14:17], v[18:21]
	v_mfma_f32_16x16x32_bf16 v[18:21], v[42:45], v[2:5], v[138:141]
	v_exp_f32_e32 v42, v40
	v_exp_f32_e32 v43, v41
	ds_read_b128 v[38:41], v94 offset:8192
	v_mfma_f32_16x16x32_bf16 v[26:29], v[34:37], v[10:13], v[138:141]
	ds_read_b128 v[34:37], v232 offset:8192
	v_exp_f32_e32 v44, v62
	v_exp_f32_e32 v45, v65
	v_mfma_f32_16x16x32_bf16 v[86:89], v[90:93], v[6:9], v[18:21]
	s_nop 2
	v_exp_f32_e32 v20, v63
	v_exp_f32_e32 v21, v64
	v_cvt_pk_bf16_f32 v18, v95, v96
	s_waitcnt lgkmcnt(0)
	v_mfma_f32_16x16x32_bf16 v[26:29], v[58:61], v[14:17], v[26:29]
	ds_read_b128 v[58:61], v233 offset:8192
	ds_read_b128 v[62:65], v94 offset:12288
	ds_read_b128 v[94:97], v234 offset:8192
	ds_read_b128 v[138:141], v232 offset:12288
	ds_read_b128 v[146:149], v233 offset:12288
	v_mfma_f32_16x16x32_bf16 v[38:41], v[38:41], v[2:5], v[150:153]
	v_cvt_pk_bf16_f32 v19, v42, v43
	v_cvt_pk_bf16_f32 v20, v44, v20
	v_cvt_pk_bf16_f32 v21, v21, v45
	v_mfma_f32_16x16x32_bf16 v[90:93], v[34:37], v[6:9], v[38:41]
	v_cvt_pk_bf16_f32 v42, v241, v230
	v_cvt_pk_bf16_f32 v43, v231, v235
	v_cvt_pk_bf16_f32 v44, v236, v237
	s_waitcnt lgkmcnt(0)
	v_mfma_f32_16x16x32_bf16 v[34:37], v[58:61], v[10:13], v[150:153]
	v_cvt_pk_bf16_f32 v45, v242, v243
	v_cvt_pk_bf16_f32 v58, v217, v218
	v_cvt_pk_bf16_f32 v59, v219, v220
	ds_read_b128 v[150:153], v234 offset:12288
	v_mfma_f32_16x16x32_bf16 v[60:63], v[62:65], v[2:5], v[142:145]
	s_waitcnt vmcnt(4) lgkmcnt(0)
	s_barrier
	v_mfma_f32_16x16x32_bf16 v[38:41], v[94:97], v[14:17], v[34:37]
	v_mfma_f32_16x16x32_bf16 v[94:97], v[138:141], v[6:9], v[60:63]
	s_nop 1
	v_cvt_pk_bf16_f32 v34, v224, v225
	v_cvt_pk_bf16_f32 v35, v239, v240
	v_cvt_pk_bf16_f32 v36, v226, v227
	v_mfma_f32_16x16x32_bf16 v[62:65], v[146:149], v[10:13], v[142:145]
	v_cvt_pk_bf16_f32 v37, v228, v229
	v_cvt_pk_bf16_f32 v60, v221, v238
	v_cvt_pk_bf16_f32 v61, v222, v223
	s_waitcnt lgkmcnt(0)
	v_mfma_f32_16x16x32_bf16 v[62:65], v[150:153], v[14:17], v[62:65]
	s_cbranch_scc0 .LBB0_522
	s_mov_b32 s2, s55
	s_mov_b32 s55, s57
	s_branch .LBB0_534
